# attention: remap workgroup->(head, q-block pair) so the 4 workgroups of a head share one XCD L2 for K/V; plus S5 XCD remap
# speedup vs baseline: 1.0104x; 1.0017x over previous
.LBB0_150:
	s_and_b32 s55, s33, 0xffffff80
	s_lshr_b32 s2, s72, 3
	s_or_b32 s10, s72, s55
	s_and_b32 vcc_lo, s10, 7
	s_lshl_b32 vcc_lo, vcc_lo, 2
	s_bfe_u32 vcc_hi, s10, 0x20003
	s_or_b32 vcc_lo, vcc_lo, vcc_hi
	s_andn2_b32 vcc_hi, s10, 0x1f
	s_or_b32 vcc_lo, vcc_lo, vcc_hi
	v_writelane_b32 v253, s2, 7
	s_lshl_b32 s2, s88, 1
	s_ashr_i32 s8, s10, 6
	v_writelane_b32 v253, s2, 8
	s_and_b32 s2, s2, 14
	s_ashr_i32 s9, s8, 31
	v_writelane_b32 v253, s2, 9
	s_ashr_i32 s6, vcc_lo, 2
	s_lshl_b64 s[2:3], s[8:9], 17
	v_writelane_b32 v253, s2, 10
	s_ashr_i32 s7, s6, 31
	s_lshl_b64 s[12:13], s[6:7], 19
	v_writelane_b32 v253, s3, 11
	s_lshl_b64 s[2:3], s[6:7], 13
	v_writelane_b32 v253, s2, 12
	s_lshl_b64 s[8:9], s[8:9], 23
	s_ashr_i32 s5, s33, 7
	v_writelane_b32 v253, s3, 13
	s_lshl_b32 s2, vcc_lo, 8
	s_and_b32 s11, s2, 0x300
	s_lshl_b32 s2, s11, 8
	s_or_b32 s12, s12, s2
	v_writelane_b32 v253, s12, 14
	s_lshl_b64 s[2:3], s[6:7], 18
	s_lshl_b32 s7, s11, 12
	v_writelane_b32 v253, s13, 15
	v_writelane_b32 v253, s7, 16
	v_writelane_b32 v253, s8, 17
	s_or_b32 s7, s11, 0xc0
	s_lshl_b32 s56, s5, 16
	v_writelane_b32 v253, s9, 18
	v_writelane_b32 v253, s11, 19
	v_writelane_b32 v253, s7, 20
	s_lshl_b32 s7, s72, 9
	s_and_b32 s4, s6, 15
	s_lshl_b32 s6, s6, 7
	s_or_b32 s7, s7, s56
	s_lshl_b32 s60, s5, 4
	s_and_b32 s6, s6, 0x780
	v_writelane_b32 v253, s7, 21
	s_add_i32 s7, s56, 0x10000
	s_add_u32 s58, s0, 0x8560200
	s_addc_u32 s59, s1, 0
	s_add_u32 s62, s0, 0x8560400
	s_addc_u32 s63, s1, 0
	s_add_u32 s64, s0, 0x8560500
	s_addc_u32 s65, s1, 0
	s_add_u32 s70, s0, 0x8560600
	s_addc_u32 s71, s1, 0
	s_add_u32 s80, s0, 0x8560700
	s_addc_u32 s81, s1, 0
	s_add_u32 s86, s0, 0x8560800
	s_addc_u32 s87, s1, 0
	s_add_u32 s90, s0, 0x8560900
	s_addc_u32 s91, s1, 0
	s_add_u32 s94, s0, 0x8560a00
	s_addc_u32 s95, s1, 0
	s_add_u32 s8, s0, 0x8560b00
	v_writelane_b32 v253, s7, 22
	s_addc_u32 s9, s1, 0
	v_writelane_b32 v253, s8, 23
	s_mov_b32 s29, 0
	s_mov_b32 s73, s29
	v_writelane_b32 v253, s9, 24
	s_add_u32 s8, s0, 0x8560c00
	s_addc_u32 s9, s1, 0
	v_writelane_b32 v253, s8, 25
	s_mov_b32 s54, 1
	v_mov_b32_e32 v209, 0
	v_writelane_b32 v253, s9, 26
	s_add_u32 s8, s0, 0x8560d00
	s_addc_u32 s9, s1, 0
	v_writelane_b32 v253, s8, 27
	s_mov_b32 s19, 0x20000
	s_brev_b32 s18, 32
	v_writelane_b32 v253, s9, 28
	s_add_u32 s8, s0, 0x8560e00
	s_addc_u32 s9, s1, 0
	v_writelane_b32 v253, s8, 29
	v_mov_b32_e32 v246, 0xc0135761
	v_mov_b32_e32 v248, 0x1000
	v_writelane_b32 v253, s9, 30
	s_add_u32 s8, s0, 0x8560f00
	s_addc_u32 s9, s1, 0
	v_writelane_b32 v253, s8, 31
	v_mov_b32_e32 v249, 0x2000
	v_mbcnt_hi_u32_b32 v250, -1, v67
	v_writelane_b32 v253, s9, 32
	s_add_u32 s8, s0, 0x8561000
	s_addc_u32 s9, s1, 0
	v_writelane_b32 v253, s8, 33
	v_mov_b32_e32 v251, 0xff800000
	s_mov_b32 s92, 0x800000
	v_writelane_b32 v253, s9, 34
	s_add_u32 s8, s0, 0x8561100
	s_addc_u32 s9, s1, 0
	v_writelane_b32 v253, s8, 35
	s_movk_i32 s93, 0x800
	s_movk_i32 s26, 0xf7ff
	v_writelane_b32 v253, s9, 36
	s_add_u32 s8, s0, 0x8561200
	s_addc_u32 s9, s1, 0
	v_writelane_b32 v253, s8, 37
	s_mov_b32 s27, 0x41000000
	s_movk_i32 s85, 0x7fff
	v_writelane_b32 v253, s9, 38
	s_add_u32 s8, s0, 0x8561300
	s_addc_u32 s9, s1, 0
	v_writelane_b32 v253, s8, 39
	s_mov_b64 s[96:97], 0x80
	s_mov_b64 s[74:75], 0x100
	v_writelane_b32 v253, s9, 40
	s_add_u32 s8, s0, 0x8563400
	s_addc_u32 s9, s1, 0
	v_writelane_b32 v253, s8, 41
	s_add_u32 s0, s0, 0x8563500
	s_addc_u32 s1, s1, 0
	v_writelane_b32 v253, s9, 42
	v_writelane_b32 v253, s0, 43
	s_nop 1
	v_writelane_b32 v253, s1, 44
	s_mul_i32 s0, s5, 0xd80
	s_addk_i32 s0, 0xd80
	s_ashr_i32 s1, s0, 31
	s_lshl_b64 s[0:1], s[0:1], 2
	v_readlane_b32 s5, v253, 4
	s_add_u32 s78, s5, s0
	v_readlane_b32 s0, v253, 5
	s_addc_u32 s79, s0, s1
	s_add_u32 s0, s78, 0x200
	s_addc_u32 s1, s79, 0
	v_writelane_b32 v253, s0, 45
	s_nop 1
	v_writelane_b32 v253, s1, 46
	s_add_u32 s0, s78, 0x1000
	s_addc_u32 s1, s79, 0
	v_writelane_b32 v253, s0, 47
	s_nop 1
	v_writelane_b32 v253, s1, 48
	s_add_u32 s0, s78, 0x1100
	s_addc_u32 s1, s79, 0
	v_writelane_b32 v253, s0, 49
	s_nop 1
	v_writelane_b32 v253, s1, 50
	s_add_u32 s0, s78, 0x1200
	s_addc_u32 s1, s79, 0
	v_writelane_b32 v253, s0, 51
	s_nop 1
	v_writelane_b32 v253, s1, 52
	s_add_u32 s0, s78, 0x1300
	s_addc_u32 s1, s79, 0
	v_writelane_b32 v253, s0, 53
	s_nop 1
	v_writelane_b32 v253, s1, 54
	s_add_u32 s0, s78, 0x3400
	s_addc_u32 s1, s79, 0
	v_writelane_b32 v253, s0, 55
	s_nop 1
	v_writelane_b32 v253, s1, 56
	s_add_u32 s0, s78, 0x3500
	s_addc_u32 s1, s79, 0
	v_writelane_b32 v253, s0, 57
	s_lshl_b64 s[2:3], s[2:3], 1
	s_nop 0
	v_writelane_b32 v253, s1, 58
	s_lshl_b32 s0, s10, 5
	v_writelane_b32 v253, s0, 59
	v_writelane_b32 v253, vcc_lo, 60
	s_lshl_b32 s0, s10, 1
	s_lshl_b32 s1, s0, 1
	s_and_b32 s1, s1, 0x1c
	s_lshr_b32 vcc_hi, s0, 3
	s_and_b32 vcc_hi, vcc_hi, 2
	s_or_b32 s1, s1, vcc_hi
	s_andn2_b32 s0, s0, 0x1f
	s_or_b32 s0, s0, s1
	s_nop 1
	v_writelane_b32 v253, s0, 61
	v_writelane_b32 v253, s0, 8
	s_lshl_b32 s0, s4, 2
	v_writelane_b32 v253, s0, 62
	v_writelane_b32 v253, s2, 63
	s_lshl_b32 s0, s6, 1
	s_mov_b32 s1, 0xffff0000
	v_writelane_b32 v254, s3, 0
	v_writelane_b32 v254, s0, 1
	s_add_i32 s0, 0, 0x20000
	v_writelane_b32 v254, s0, 2
	s_add_i32 s0, 0, 0x23fc8
	v_writelane_b32 v254, s0, 3
	s_add_i32 s0, 0, 0x23fcc
	v_writelane_b32 v254, s0, 4
	s_add_i32 s0, 0, 0x23fc0
	v_writelane_b32 v254, s0, 5
	s_add_i32 s0, 0, 0x23fc4
	v_writelane_b32 v254, s0, 6
	v_writelane_b32 v254, s60, 7
	v_writelane_b32 v254, s76, 8
	s_mov_b32 s0, 0x3e0293ee
	s_nop 0
	v_writelane_b32 v254, s77, 9
	v_writelane_b32 v254, s55, 10
	v_writelane_b32 v254, s56, 11
	v_writelane_b32 v254, s58, 12
	s_nop 1
	v_writelane_b32 v254, s59, 13
	v_writelane_b32 v254, s62, 14
	s_nop 1
	v_writelane_b32 v254, s63, 15
	v_writelane_b32 v254, s64, 16
	s_nop 1
	v_writelane_b32 v254, s65, 17
	v_writelane_b32 v254, s70, 18
	s_nop 1
	v_writelane_b32 v254, s71, 19
	v_writelane_b32 v254, s80, 20
	s_nop 1
	v_writelane_b32 v254, s81, 21
	v_writelane_b32 v254, s86, 22
	s_nop 1
	v_writelane_b32 v254, s87, 23
	v_writelane_b32 v254, s90, 24
	s_nop 1
	v_writelane_b32 v254, s91, 25
	v_writelane_b32 v254, s94, 26
	s_nop 1
	v_writelane_b32 v254, s95, 27
	s_branch .LBB0_152
